# attention QK^T MFMAs in snake order (accumulator or Q fragment shared at every transition), GEMM snake, P16 warm-up
# baseline (speedup 1.0000x reference)
.LBB0_542:
	v_add_u32_e32 v192, s8, v212
	ds_read_b64_tr_b16 v[178:179], v192 offset:24576
	ds_read_b64_tr_b16 v[180:181], v192 offset:25088
	s_waitcnt lgkmcnt(9)
	v_mfma_f32_32x32x16_f16 v[98:113], v[174:177], v[138:141], v[34:49]
	v_add_f32_e32 v82, v66, v67
	v_add_f32_e32 v82, v68, v82
	v_add_f32_e32 v82, v69, v82
	v_add_f32_e32 v82, v70, v82
	v_add_f32_e32 v82, v71, v82
	v_cvt_pk_f16_f32 v142, v66, v67
	v_cvt_pk_f16_f32 v143, v68, v69
	ds_read_b64_tr_b16 v[174:175], v192 offset:28672
	ds_read_b64_tr_b16 v[176:177], v192 offset:29184
	v_add_f32_e32 v66, v72, v82
	s_waitcnt lgkmcnt(10)
	v_mfma_f32_32x32x16_f16 v[82:97], v[170:173], v[138:141], v[34:49]
	v_add_f32_e32 v66, v73, v66
	v_add_f32_e32 v66, v74, v66
	v_add_f32_e32 v122, v75, v66
	v_cvt_pk_f16_f32 v144, v70, v71
	v_cvt_pk_f16_f32 v145, v72, v73
	ds_read_b64_tr_b16 v[66:67], v192 offset:25600
	ds_read_b64_tr_b16 v[68:69], v192 offset:26112
	s_waitcnt lgkmcnt(11)
	v_mfma_f32_32x32x16_f16 v[82:97], v[162:165], v[130:133], v[82:97]
	v_add_f32_e32 v70, v76, v122
	v_add_f32_e32 v70, v77, v70
	v_add_f32_e32 v70, v78, v70
	v_add_f32_e32 v122, v79, v70
	v_cvt_pk_f16_f32 v134, v74, v75
	v_cvt_pk_f16_f32 v135, v76, v77
	ds_read_b64_tr_b16 v[70:71], v192 offset:29696
	ds_read_b64_tr_b16 v[72:73], v192 offset:30208
	s_waitcnt lgkmcnt(12)
	v_mfma_f32_32x32x16_f16 v[98:113], v[166:169], v[130:133], v[98:113]
	v_add_f32_e32 v74, v80, v122
	v_add_f32_e32 v74, v81, v74
	v_add_f32_e32 v74, v50, v74
	v_add_f32_e32 v122, v51, v74
	v_cvt_pk_f16_f32 v136, v78, v79
	v_cvt_pk_f16_f32 v137, v80, v81
	ds_read_b64_tr_b16 v[74:75], v192 offset:26624
	ds_read_b64_tr_b16 v[76:77], v192 offset:27136
	s_waitcnt lgkmcnt(13)
	v_mfma_f32_32x32x16_f16 v[98:113], v[158:161], v[118:121], v[98:113]
	v_add_f32_e32 v78, v52, v122
	v_add_f32_e32 v78, v53, v78
	v_add_f32_e32 v78, v54, v78
	v_add_f32_e32 v78, v55, v78
	v_cvt_pk_f16_f32 v126, v50, v51
	v_cvt_pk_f16_f32 v127, v52, v53
	ds_read_b64_tr_b16 v[50:51], v192 offset:30720
	ds_read_b64_tr_b16 v[52:53], v192 offset:31232
	s_waitcnt lgkmcnt(14)
	v_mfma_f32_32x32x16_f16 v[82:97], v[154:157], v[118:121], v[82:97]
	v_add_f32_e32 v78, v56, v78
	v_add_f32_e32 v78, v57, v78
	v_add_f32_e32 v78, v58, v78
	v_add_f32_e32 v78, v59, v78
	v_cvt_pk_f16_f32 v128, v54, v55
	v_cvt_pk_f16_f32 v129, v56, v57
	ds_read_b64_tr_b16 v[54:55], v192 offset:27648
	ds_read_b64_tr_b16 v[56:57], v192 offset:28160
	s_waitcnt lgkmcnt(14)
	v_mfma_f32_32x32x16_f16 v[82:97], v[146:149], v[114:117], v[82:97]
	v_add_f32_e32 v78, v60, v78
	v_add_f32_e32 v78, v61, v78
	v_add_f32_e32 v78, v62, v78
	v_add_f32_e32 v78, v63, v78
	v_cvt_pk_f16_f32 v122, v58, v59
	v_cvt_pk_f16_f32 v123, v60, v61
	ds_read_b64_tr_b16 v[58:59], v192 offset:31744
	ds_read_b64_tr_b16 v[60:61], v192 offset:32256
	v_mfma_f32_32x32x16_f16 v[98:113], v[150:153], v[114:117], v[98:113]
	v_add_f32_e32 v78, v64, v78
	v_add_f32_e32 v78, v65, v78
	v_add_f32_e32 v78, 0, v78
	v_cvt_pk_f16_f32 v124, v62, v63
	v_cvt_pk_f16_f32 v125, v64, v65
	v_lshl_add_u64 v[62:63], v[188:189], 0, s[54:55]
	s_add_i32 s8, s11, s76
	s_mov_b32 s9, m0
	s_mov_b32 m0, s8
	s_nop 0
	global_load_lds_dwordx4 v[62:63], off
	s_mov_b32 m0, s9
	v_lshl_add_u64 v[62:63], v[186:187], 0, s[54:55]
	s_add_i32 s8, s30, s77
	s_mov_b32 s9, m0
	s_mov_b32 m0, s8
	s_nop 0
	global_load_lds_dwordx4 v[62:63], off
	s_mov_b32 m0, s9
	v_max_f32_e32 v62, v99, v99
	v_max_f32_e32 v63, v98, v98
	v_max_f32_e32 v62, v63, v62
	v_max3_f32 v63, v100, v101, v83
	v_max3_f32 v62, v62, v82, v84
	v_max3_f32 v62, v62, v85, v102
	v_max3_f32 v63, v63, v104, v105
	v_max3_f32 v62, v62, v103, v86
	v_max3_f32 v63, v63, v88, v89
	v_max3_f32 v62, v62, v87, v106
	v_max3_f32 v63, v63, v108, v109
	v_max3_f32 v62, v62, v107, v90
	v_max3_f32 v63, v63, v92, v93
	v_max3_f32 v62, v62, v91, v110
	v_max3_f32 v63, v63, v112, v113
	v_max3_f32 v62, v62, v111, v94
	v_max3_f32 v63, v63, v96, v97
	v_max3_f32 v62, v62, v95, v63
	v_mov_b32_e32 v63, v62
	s_nop 1
	v_permlane32_swap_b32_e32 v62, v63
	v_max_f32_e32 v63, v63, v63
	v_max_f32_e32 v62, v62, v62
	v_max_f32_e32 v62, v62, v63
	v_cmp_lt_f32_e32 vcc, s81, v62
	s_cmp_lg_u64 vcc, 0
	v_add_f32_e32 v193, v214, v78
	s_cselect_b64 s[8:9], -1, 0
	s_cbranch_vccnz .LBB0_552

.LBB0_547:
	v_add_u32_e32 v194, s11, v212
	ds_read_b64_tr_b16 v[150:151], v194 offset:24576
	ds_read_b64_tr_b16 v[152:153], v194 offset:25088
	s_add_i32 s8, s30, 0x2000
	s_cmpk_lg_i32 s30, 0x4000
	s_cselect_b32 s11, s8, 0
	s_waitcnt lgkmcnt(9)
	v_mfma_f32_32x32x16_f16 v[66:81], v[62:65], v[138:141], v[34:49]
	v_add_f32_e32 v50, v98, v99
	v_add_f32_e32 v50, v100, v50
	v_add_f32_e32 v50, v101, v50
	v_add_f32_e32 v50, v102, v50
	v_add_f32_e32 v50, v103, v50
	v_cvt_pk_f16_f32 v142, v98, v99
	v_cvt_pk_f16_f32 v143, v100, v101
	ds_read_b64_tr_b16 v[154:155], v194 offset:28672
	ds_read_b64_tr_b16 v[156:157], v194 offset:29184
	v_add_f32_e32 v50, v104, v50
	v_add_f32_e32 v50, v105, v50
	v_add_f32_e32 v50, v106, v50
	v_add_f32_e32 v122, v107, v50
	s_waitcnt lgkmcnt(10)
	v_mfma_f32_32x32x16_f16 v[50:65], v[174:177], v[138:141], v[34:49]
	v_cvt_pk_f16_f32 v144, v102, v103
	v_cvt_pk_f16_f32 v145, v104, v105
	ds_read_b64_tr_b16 v[98:99], v194 offset:25600
	ds_read_b64_tr_b16 v[100:101], v194 offset:26112
	s_waitcnt lgkmcnt(11)
	v_mfma_f32_32x32x16_f16 v[50:65], v[170:173], v[130:133], v[50:65]
	v_add_f32_e32 v102, v108, v122
	v_add_f32_e32 v102, v109, v102
	v_add_f32_e32 v102, v110, v102
	v_add_f32_e32 v122, v111, v102
	v_cvt_pk_f16_f32 v134, v106, v107
	v_cvt_pk_f16_f32 v135, v108, v109
	ds_read_b64_tr_b16 v[102:103], v194 offset:29696
	ds_read_b64_tr_b16 v[104:105], v194 offset:30208
	s_waitcnt lgkmcnt(12)
	v_mfma_f32_32x32x16_f16 v[66:81], v[178:181], v[130:133], v[66:81]
	v_add_f32_e32 v106, v112, v122
	v_add_f32_e32 v106, v113, v106
	v_add_f32_e32 v106, v82, v106
	v_add_f32_e32 v122, v83, v106
	v_cvt_pk_f16_f32 v136, v110, v111
	v_cvt_pk_f16_f32 v137, v112, v113
	ds_read_b64_tr_b16 v[106:107], v194 offset:26624
	ds_read_b64_tr_b16 v[108:109], v194 offset:27136
	s_waitcnt lgkmcnt(13)
	v_mfma_f32_32x32x16_f16 v[66:81], v[166:169], v[118:121], v[66:81]
	v_add_f32_e32 v110, v84, v122
	v_add_f32_e32 v110, v85, v110
	v_add_f32_e32 v110, v86, v110
	v_add_f32_e32 v110, v87, v110
	v_cvt_pk_f16_f32 v126, v82, v83
	v_cvt_pk_f16_f32 v127, v84, v85
	ds_read_b64_tr_b16 v[82:83], v194 offset:30720
	ds_read_b64_tr_b16 v[84:85], v194 offset:31232
	s_waitcnt lgkmcnt(14)
	v_mfma_f32_32x32x16_f16 v[50:65], v[162:165], v[118:121], v[50:65]
	v_add_f32_e32 v110, v88, v110
	v_add_f32_e32 v110, v89, v110
	v_add_f32_e32 v110, v90, v110
	v_add_f32_e32 v110, v91, v110
	v_cvt_pk_f16_f32 v128, v86, v87
	v_cvt_pk_f16_f32 v129, v88, v89
	ds_read_b64_tr_b16 v[86:87], v194 offset:27648
	ds_read_b64_tr_b16 v[88:89], v194 offset:28160
	s_waitcnt lgkmcnt(14)
	v_mfma_f32_32x32x16_f16 v[50:65], v[146:149], v[114:117], v[50:65]
	v_add_f32_e32 v110, v92, v110
	v_add_f32_e32 v110, v93, v110
	v_add_f32_e32 v110, v94, v110
	v_add_f32_e32 v110, v95, v110
	v_cvt_pk_f16_f32 v122, v90, v91
	v_cvt_pk_f16_f32 v123, v92, v93
	ds_read_b64_tr_b16 v[90:91], v194 offset:31744
	ds_read_b64_tr_b16 v[92:93], v194 offset:32256
	v_mfma_f32_32x32x16_f16 v[66:81], v[158:161], v[114:117], v[66:81]
	v_add_f32_e32 v110, v96, v110
	v_add_f32_e32 v110, v97, v110
	v_add_f32_e32 v110, 0, v110
	v_cvt_pk_f16_f32 v124, v94, v95
	v_cvt_pk_f16_f32 v125, v96, v97
	v_max_f32_e32 v94, v67, v67
	v_max_f32_e32 v95, v66, v66
	v_max_f32_e32 v94, v95, v94
	s_nop 3
	v_max3_f32 v95, v68, v69, v51
	v_max3_f32 v94, v94, v50, v52
	v_max3_f32 v94, v94, v53, v70
	v_max3_f32 v95, v95, v72, v73
	v_max3_f32 v94, v94, v71, v54
	v_max3_f32 v95, v95, v56, v57
	v_max3_f32 v94, v94, v55, v74
	v_max3_f32 v95, v95, v76, v77
	v_max3_f32 v94, v94, v75, v58
	v_max3_f32 v95, v95, v60, v61
	v_max3_f32 v94, v94, v59, v78
	v_max3_f32 v95, v95, v80, v81
	v_max3_f32 v94, v94, v79, v62
	v_max3_f32 v95, v95, v64, v65
	v_max3_f32 v94, v94, v63, v95
	v_mov_b32_e32 v95, v94
	s_nop 1
	v_permlane32_swap_b32_e32 v94, v95
	v_max_f32_e32 v95, v95, v95
	v_max_f32_e32 v94, v94, v94
	s_add_i32 s8, s30, s76
	s_mov_b32 s9, m0
	s_mov_b32 m0, s8
	s_nop 0
	global_load_lds_dwordx4 v[188:189], off
	s_mov_b32 m0, s9
	v_max_f32_e32 v94, v94, v95
	s_add_i32 s8, s11, s77
	s_mov_b32 s9, m0
	s_mov_b32 m0, s8
	s_nop 0
	global_load_lds_dwordx4 v[186:187], off
	s_mov_b32 m0, s9
	v_cmp_lt_f32_e32 vcc, s81, v94
	s_cmp_lg_u64 vcc, 0
	v_add_f32_e32 v214, v193, v110
	s_cselect_b64 s[8:9], -1, 0
	s_cbranch_vccnz .LBB0_555

; __device__ __forceinline__ void cmask(f32x16& p0, f32x16& p1, int jb, int qrel, int hi) {
;     const float NEG = -INFINITY; int kb = 64 * jb + 4 * hi;
; #pragma unroll
;     for (int r = 0; r < 16; ++r) { int kv = kb + (r & 3) + 8 * (r >> 2); if (kv > qrel) p0[r] = NEG; if (kv + 32 > qrel) p1[r] = NEG; }
; }
.LBB0_560:
	v_add_u32_e32 v112, s68, v212
	ds_read_b64_tr_b16 v[98:99], v112 offset:24576
	ds_read_b64_tr_b16 v[100:101], v112 offset:25088
	v_add_f32_e32 v82, v66, v67
	v_add_f32_e32 v82, v68, v82
	v_add_f32_e32 v82, v69, v82
	v_add_f32_e32 v82, v70, v82
	v_add_f32_e32 v102, v71, v82
	s_waitcnt lgkmcnt(9)
	v_mfma_f32_32x32x16_f16 v[82:97], v[174:177], v[138:141], v[34:49]
	v_cvt_pk_f16_f32 v142, v66, v67
	v_cvt_pk_f16_f32 v143, v68, v69
	ds_read_b64_tr_b16 v[66:67], v112 offset:28672
	ds_read_b64_tr_b16 v[68:69], v112 offset:29184
	s_waitcnt lgkmcnt(10)
	v_mfma_f32_32x32x16_f16 v[34:49], v[170:173], v[138:141], v[34:49]
	v_add_f32_e32 v102, v72, v102
	v_add_f32_e32 v102, v73, v102
	v_add_f32_e32 v102, v74, v102
	v_add_f32_e32 v102, v75, v102
	v_cvt_pk_f16_f32 v144, v70, v71
	v_cvt_pk_f16_f32 v145, v72, v73
	ds_read_b64_tr_b16 v[70:71], v112 offset:25600
	ds_read_b64_tr_b16 v[72:73], v112 offset:26112
	s_waitcnt lgkmcnt(11)
	v_mfma_f32_32x32x16_f16 v[34:49], v[162:165], v[130:133], v[34:49]
	v_add_f32_e32 v102, v76, v102
	v_add_f32_e32 v102, v77, v102
	v_add_f32_e32 v102, v78, v102
	v_add_f32_e32 v102, v79, v102
	v_cvt_pk_f16_f32 v134, v74, v75
	v_cvt_pk_f16_f32 v135, v76, v77
	ds_read_b64_tr_b16 v[74:75], v112 offset:29696
	ds_read_b64_tr_b16 v[76:77], v112 offset:30208
	s_waitcnt lgkmcnt(12)
	v_mfma_f32_32x32x16_f16 v[82:97], v[166:169], v[130:133], v[82:97]
	v_add_f32_e32 v102, v80, v102
	v_add_f32_e32 v102, v81, v102
	v_add_f32_e32 v102, v50, v102
	v_add_f32_e32 v102, v51, v102
	v_cvt_pk_f16_f32 v136, v78, v79
	v_cvt_pk_f16_f32 v137, v80, v81
	ds_read_b64_tr_b16 v[78:79], v112 offset:26624
	ds_read_b64_tr_b16 v[80:81], v112 offset:27136
	s_waitcnt lgkmcnt(13)
	v_mfma_f32_32x32x16_f16 v[82:97], v[158:161], v[118:121], v[82:97]
	v_add_f32_e32 v102, v52, v102
	v_add_f32_e32 v102, v53, v102
	v_add_f32_e32 v102, v54, v102
	v_add_f32_e32 v106, v55, v102
	v_cvt_pk_f16_f32 v126, v50, v51
	v_cvt_pk_f16_f32 v127, v52, v53
	ds_read_b64_tr_b16 v[102:103], v112 offset:30720
	ds_read_b64_tr_b16 v[104:105], v112 offset:31232
	s_waitcnt lgkmcnt(14)
	v_mfma_f32_32x32x16_f16 v[34:49], v[154:157], v[118:121], v[34:49]
	v_add_f32_e32 v50, v56, v106
	v_add_f32_e32 v50, v57, v50
	v_add_f32_e32 v50, v58, v50
	v_add_f32_e32 v50, v59, v50
	v_cvt_pk_f16_f32 v128, v54, v55
	v_cvt_pk_f16_f32 v129, v56, v57
	ds_read_b64_tr_b16 v[106:107], v112 offset:27648
	ds_read_b64_tr_b16 v[108:109], v112 offset:28160
	s_waitcnt lgkmcnt(14)
	v_mfma_f32_32x32x16_f16 v[34:49], v[146:149], v[114:117], v[34:49]
	v_add_f32_e32 v50, v60, v50
	v_add_f32_e32 v50, v61, v50
	v_add_f32_e32 v50, v62, v50
	v_add_f32_e32 v50, v63, v50
	v_cvt_pk_f16_f32 v122, v58, v59
	v_cvt_pk_f16_f32 v123, v60, v61
	ds_read_b64_tr_b16 v[110:111], v112 offset:31744
	ds_read_b64_tr_b16 v[112:113], v112 offset:32256
	v_mfma_f32_32x32x16_f16 v[82:97], v[150:153], v[114:117], v[82:97]
	v_add_f32_e32 v50, v64, v50
	v_add_f32_e32 v50, v65, v50
	v_add_f32_e32 v50, 0, v50
	v_cvt_pk_f16_f32 v124, v62, v63
	v_cvt_pk_f16_f32 v125, v64, v65
	s_cmp_gt_i32 s29, 7
	s_cbranch_scc1 .LBB0_562
	v_mov_b32_e32 v51, v190
	v_or_b32_e32 v53, 0xe0, v208
	v_add_u32_e32 v51, s89, v51
	v_or_b32_e32 v52, 0xc0, v208
	v_cmp_le_i32_e32 vcc, v53, v51
	s_nop 1
	v_cndmask_b32_e32 v34, v200, v34, vcc
	v_cmp_lt_i32_e32 vcc, v52, v51
	s_nop 1
	v_cndmask_b32_e32 v83, v200, v83, vcc
	v_cmp_le_i32_e32 vcc, v52, v51
	v_or_b32_e32 v52, 0xe1, v208
	s_nop 0
	v_cndmask_b32_e32 v82, v200, v82, vcc
	v_cmp_le_i32_e32 vcc, v52, v51
	v_or_b32_e32 v52, 0xc2, v208
	s_nop 0
	v_cndmask_b32_e32 v35, v200, v35, vcc
	v_cmp_le_i32_e32 vcc, v52, v51
	v_or_b32_e32 v52, 0xe2, v208
	s_nop 0
	v_cndmask_b32_e32 v84, v200, v84, vcc
	v_cmp_le_i32_e32 vcc, v52, v51
	v_or_b32_e32 v52, 0xc3, v208
	s_nop 0
	v_cndmask_b32_e32 v36, v200, v36, vcc
	v_cmp_le_i32_e32 vcc, v52, v51
	v_or_b32_e32 v52, 0xe3, v208
	s_nop 0
	v_cndmask_b32_e32 v85, v200, v85, vcc
	v_cmp_le_i32_e32 vcc, v52, v51
	v_or_b32_e32 v52, 0xc8, v208
	s_nop 0
	v_cndmask_b32_e32 v37, v200, v37, vcc
	v_cmp_le_i32_e32 vcc, v52, v51
	v_or_b32_e32 v52, 0xe8, v208
	s_nop 0
	v_cndmask_b32_e32 v86, v200, v86, vcc
	v_cmp_le_i32_e32 vcc, v52, v51
	v_or_b32_e32 v52, 0xc9, v208
	s_nop 0
	v_cndmask_b32_e32 v38, v200, v38, vcc
	v_cmp_le_i32_e32 vcc, v52, v51
	v_or_b32_e32 v52, 0xe9, v208
	s_nop 0
	v_cndmask_b32_e32 v87, v200, v87, vcc
	v_cmp_le_i32_e32 vcc, v52, v51
	v_or_b32_e32 v52, 0xca, v208
	s_nop 0
	v_cndmask_b32_e32 v39, v200, v39, vcc
	v_cmp_le_i32_e32 vcc, v52, v51
	v_or_b32_e32 v52, 0xea, v208
	s_nop 0
	v_cndmask_b32_e32 v88, v200, v88, vcc
	v_cmp_le_i32_e32 vcc, v52, v51
	v_or_b32_e32 v52, 0xcb, v208
	s_nop 0
	v_cndmask_b32_e32 v40, v200, v40, vcc
	v_cmp_le_i32_e32 vcc, v52, v51
	v_or_b32_e32 v52, 0xeb, v208
	s_nop 0
	v_cndmask_b32_e32 v89, v200, v89, vcc
	v_cmp_le_i32_e32 vcc, v52, v51
	v_or_b32_e32 v52, 0xd0, v208
	s_nop 0
	v_cndmask_b32_e32 v41, v200, v41, vcc
	v_cmp_le_i32_e32 vcc, v52, v51
	v_or_b32_e32 v52, 0xf0, v208
	s_nop 0
	v_cndmask_b32_e32 v90, v200, v90, vcc
	v_cmp_le_i32_e32 vcc, v52, v51
	v_or_b32_e32 v52, 0xd1, v208
	s_nop 0
	v_cndmask_b32_e32 v42, v200, v42, vcc
	v_cmp_le_i32_e32 vcc, v52, v51
	v_or_b32_e32 v52, 0xf1, v208
	s_nop 0
	v_cndmask_b32_e32 v91, v200, v91, vcc
	v_cmp_le_i32_e32 vcc, v52, v51
	v_or_b32_e32 v52, 0xd2, v208
	s_nop 0
	v_cndmask_b32_e32 v43, v200, v43, vcc
	v_cmp_le_i32_e32 vcc, v52, v51
	v_or_b32_e32 v52, 0xf2, v208
	s_nop 0
	v_cndmask_b32_e32 v92, v200, v92, vcc
	v_cmp_le_i32_e32 vcc, v52, v51
	v_or_b32_e32 v52, 0xd3, v208
	s_nop 0
	v_cndmask_b32_e32 v44, v200, v44, vcc
	v_cmp_le_i32_e32 vcc, v52, v51
	v_or_b32_e32 v52, 0xf3, v208
	s_nop 0
	v_cndmask_b32_e32 v93, v200, v93, vcc
	v_cmp_le_i32_e32 vcc, v52, v51
	v_or_b32_e32 v52, 0xd8, v208
	s_nop 0
	v_cndmask_b32_e32 v45, v200, v45, vcc
	v_cmp_le_i32_e32 vcc, v52, v51
	v_or_b32_e32 v52, 0xf8, v208
	s_nop 0
	v_cndmask_b32_e32 v94, v200, v94, vcc
	v_cmp_le_i32_e32 vcc, v52, v51
	v_or_b32_e32 v52, 0xd9, v208
	s_nop 0
	v_cndmask_b32_e32 v46, v200, v46, vcc
	v_cmp_le_i32_e32 vcc, v52, v51
	v_or_b32_e32 v52, 0xf9, v208
	s_nop 0
	v_cndmask_b32_e32 v95, v200, v95, vcc
	v_cmp_le_i32_e32 vcc, v52, v51
	v_or_b32_e32 v52, 0xda, v208
	s_nop 0
	v_cndmask_b32_e32 v47, v200, v47, vcc
	v_cmp_le_i32_e32 vcc, v52, v51
	v_or_b32_e32 v52, 0xfa, v208
	s_nop 0
	v_cndmask_b32_e32 v96, v200, v96, vcc
	v_cmp_le_i32_e32 vcc, v52, v51
	v_or_b32_e32 v52, 0xdb, v208
	s_nop 0
	v_cndmask_b32_e32 v48, v200, v48, vcc
	v_cmp_le_i32_e32 vcc, v52, v51
	v_or_b32_e32 v52, 0xfb, v208
	s_nop 0
	v_cndmask_b32_e32 v97, v200, v97, vcc
	v_cmp_le_i32_e32 vcc, v52, v51
	s_nop 1
	v_cndmask_b32_e32 v49, v200, v49, vcc

.LBB0_571:
	v_add_u32_e32 v182, s30, v212
	ds_read_b64_tr_b16 v[178:179], v182 offset:24576
	ds_read_b64_tr_b16 v[180:181], v182 offset:25088
	s_waitcnt lgkmcnt(9)
	v_mfma_f32_32x32x16_f16 v[98:113], v[174:177], v[138:141], v[34:49]
	v_add_f32_e32 v82, v66, v67
	v_add_f32_e32 v82, v68, v82
	v_add_f32_e32 v82, v69, v82
	v_add_f32_e32 v82, v70, v82
	v_add_f32_e32 v82, v71, v82
	v_cvt_pk_f16_f32 v142, v66, v67
	v_cvt_pk_f16_f32 v143, v68, v69
	ds_read_b64_tr_b16 v[174:175], v182 offset:28672
	ds_read_b64_tr_b16 v[176:177], v182 offset:29184
	v_add_f32_e32 v66, v72, v82
	s_waitcnt lgkmcnt(10)
	v_mfma_f32_32x32x16_f16 v[82:97], v[170:173], v[138:141], v[34:49]
	v_add_f32_e32 v66, v73, v66
	v_add_f32_e32 v66, v74, v66
	v_add_f32_e32 v122, v75, v66
	v_cvt_pk_f16_f32 v144, v70, v71
	v_cvt_pk_f16_f32 v145, v72, v73
	ds_read_b64_tr_b16 v[66:67], v182 offset:25600
	ds_read_b64_tr_b16 v[68:69], v182 offset:26112
	s_waitcnt lgkmcnt(11)
	v_mfma_f32_32x32x16_f16 v[82:97], v[162:165], v[130:133], v[82:97]
	v_add_f32_e32 v70, v76, v122
	v_add_f32_e32 v70, v77, v70
	v_add_f32_e32 v70, v78, v70
	v_add_f32_e32 v122, v79, v70
	v_cvt_pk_f16_f32 v134, v74, v75
	v_cvt_pk_f16_f32 v135, v76, v77
	ds_read_b64_tr_b16 v[70:71], v182 offset:29696
	ds_read_b64_tr_b16 v[72:73], v182 offset:30208
	s_waitcnt lgkmcnt(12)
	v_mfma_f32_32x32x16_f16 v[98:113], v[166:169], v[130:133], v[98:113]
	v_add_f32_e32 v74, v80, v122
	v_add_f32_e32 v74, v81, v74
	v_add_f32_e32 v74, v50, v74
	v_add_f32_e32 v122, v51, v74
	v_cvt_pk_f16_f32 v136, v78, v79
	v_cvt_pk_f16_f32 v137, v80, v81
	ds_read_b64_tr_b16 v[74:75], v182 offset:26624
	ds_read_b64_tr_b16 v[76:77], v182 offset:27136
	s_waitcnt lgkmcnt(13)
	v_mfma_f32_32x32x16_f16 v[98:113], v[158:161], v[118:121], v[98:113]
	v_add_f32_e32 v78, v52, v122
	v_add_f32_e32 v78, v53, v78
	v_add_f32_e32 v78, v54, v78
	v_add_f32_e32 v78, v55, v78
	v_cvt_pk_f16_f32 v126, v50, v51
	v_cvt_pk_f16_f32 v127, v52, v53
	ds_read_b64_tr_b16 v[50:51], v182 offset:30720
	ds_read_b64_tr_b16 v[52:53], v182 offset:31232
	s_waitcnt lgkmcnt(14)
	v_mfma_f32_32x32x16_f16 v[82:97], v[154:157], v[118:121], v[82:97]
	v_add_f32_e32 v78, v56, v78
	v_add_f32_e32 v78, v57, v78
	v_add_f32_e32 v78, v58, v78
	v_add_f32_e32 v78, v59, v78
	v_cvt_pk_f16_f32 v128, v54, v55
	v_cvt_pk_f16_f32 v129, v56, v57
	ds_read_b64_tr_b16 v[54:55], v182 offset:27648
	ds_read_b64_tr_b16 v[56:57], v182 offset:28160
	s_waitcnt lgkmcnt(14)
	v_mfma_f32_32x32x16_f16 v[82:97], v[146:149], v[114:117], v[82:97]
	v_add_f32_e32 v78, v60, v78
	v_add_f32_e32 v78, v61, v78
	v_add_f32_e32 v78, v62, v78
	v_add_f32_e32 v78, v63, v78
	v_cvt_pk_f16_f32 v122, v58, v59
	v_cvt_pk_f16_f32 v123, v60, v61
	ds_read_b64_tr_b16 v[58:59], v182 offset:31744
	ds_read_b64_tr_b16 v[60:61], v182 offset:32256
	v_mfma_f32_32x32x16_f16 v[98:113], v[150:153], v[114:117], v[98:113]
	v_add_f32_e32 v78, v64, v78
	v_add_f32_e32 v78, v65, v78
	v_add_f32_e32 v78, 0, v78
	v_cvt_pk_f16_f32 v124, v62, v63
	v_cvt_pk_f16_f32 v125, v64, v65
	s_add_i32 s4, s40, 3
	s_cmp_ge_u32 s4, s35
	s_cselect_b64 s[70:71], -1, 0
	s_and_b64 vcc, exec, s[70:71]
	s_cbranch_vccnz .LBB0_573
	v_lshl_add_u64 v[62:63], v[194:195], 0, s[54:55]
	s_add_i32 s4, s11, s76
	s_mov_b32 s5, m0
	s_mov_b32 m0, s4
	s_nop 0
	global_load_lds_dwordx4 v[62:63], off
	s_mov_b32 m0, s5

.LBB0_587:
	v_add_u32_e32 v216, s11, v212
	ds_read_b64_tr_b16 v[186:187], v216 offset:24576
	ds_read_b64_tr_b16 v[188:189], v216 offset:25088
	s_waitcnt lgkmcnt(9)
	v_mfma_f32_32x32x16_f16 v[66:81], v[174:177], v[138:141], v[34:49]
	v_add_f32_e32 v50, v98, v99
	v_add_f32_e32 v50, v100, v50
	v_add_f32_e32 v50, v101, v50
	v_add_f32_e32 v50, v102, v50
	v_add_f32_e32 v50, v103, v50
	v_cvt_pk_f16_f32 v142, v98, v99
	v_cvt_pk_f16_f32 v143, v100, v101
	ds_read_b64_tr_b16 v[182:183], v216 offset:28672
	ds_read_b64_tr_b16 v[184:185], v216 offset:29184
	v_add_f32_e32 v50, v104, v50
	v_add_f32_e32 v50, v105, v50
	v_add_f32_e32 v50, v106, v50
	v_add_f32_e32 v98, v107, v50
	s_waitcnt lgkmcnt(10)
	v_mfma_f32_32x32x16_f16 v[50:65], v[170:173], v[138:141], v[34:49]
	v_cvt_pk_f16_f32 v144, v102, v103
	v_cvt_pk_f16_f32 v145, v104, v105
	ds_read_b64_tr_b16 v[178:179], v216 offset:25600
	ds_read_b64_tr_b16 v[180:181], v216 offset:26112
	s_waitcnt lgkmcnt(11)
	v_mfma_f32_32x32x16_f16 v[50:65], v[162:165], v[130:133], v[50:65]
	v_add_f32_e32 v98, v108, v98
	v_add_f32_e32 v98, v109, v98
	v_add_f32_e32 v98, v110, v98
	v_add_f32_e32 v98, v111, v98
	v_cvt_pk_f16_f32 v134, v106, v107
	v_cvt_pk_f16_f32 v135, v108, v109
	ds_read_b64_tr_b16 v[106:107], v216 offset:29696
	ds_read_b64_tr_b16 v[108:109], v216 offset:30208
	s_waitcnt lgkmcnt(12)
	v_mfma_f32_32x32x16_f16 v[66:81], v[166:169], v[130:133], v[66:81]
	v_add_f32_e32 v98, v112, v98
	v_add_f32_e32 v98, v113, v98
	v_add_f32_e32 v98, v82, v98
	v_add_f32_e32 v98, v83, v98
	v_cvt_pk_f16_f32 v136, v110, v111
	v_cvt_pk_f16_f32 v137, v112, v113
	ds_read_b64_tr_b16 v[102:103], v216 offset:26624
	ds_read_b64_tr_b16 v[104:105], v216 offset:27136
	s_waitcnt lgkmcnt(13)
	v_mfma_f32_32x32x16_f16 v[66:81], v[158:161], v[118:121], v[66:81]
	v_add_f32_e32 v98, v84, v98
	v_add_f32_e32 v98, v85, v98
	v_add_f32_e32 v98, v86, v98
	v_add_f32_e32 v110, v87, v98
	v_cvt_pk_f16_f32 v126, v82, v83
	v_cvt_pk_f16_f32 v127, v84, v85
	ds_read_b64_tr_b16 v[98:99], v216 offset:30720
	ds_read_b64_tr_b16 v[100:101], v216 offset:31232
	s_waitcnt lgkmcnt(14)
	v_mfma_f32_32x32x16_f16 v[50:65], v[154:157], v[118:121], v[50:65]
	v_add_f32_e32 v82, v88, v110
	v_add_f32_e32 v82, v89, v82
	v_add_f32_e32 v82, v90, v82
	v_add_f32_e32 v82, v91, v82
	v_cvt_pk_f16_f32 v128, v86, v87
	v_cvt_pk_f16_f32 v129, v88, v89
	ds_read_b64_tr_b16 v[86:87], v216 offset:27648
	ds_read_b64_tr_b16 v[88:89], v216 offset:28160
	s_waitcnt lgkmcnt(14)
	v_mfma_f32_32x32x16_f16 v[50:65], v[146:149], v[114:117], v[50:65]
	v_add_f32_e32 v82, v92, v82
	v_add_f32_e32 v82, v93, v82
	v_add_f32_e32 v82, v94, v82
	v_add_f32_e32 v110, v95, v82
	v_cvt_pk_f16_f32 v122, v90, v91
	v_cvt_pk_f16_f32 v123, v92, v93
	ds_read_b64_tr_b16 v[82:83], v216 offset:31744
	ds_read_b64_tr_b16 v[84:85], v216 offset:32256
	v_mfma_f32_32x32x16_f16 v[66:81], v[150:153], v[114:117], v[66:81]
	v_add_f32_e32 v90, v96, v110
	v_add_f32_e32 v90, v97, v90
	v_add_f32_e32 v90, 0, v90
	v_cvt_pk_f16_f32 v124, v94, v95
	v_cvt_pk_f16_f32 v125, v96, v97
	s_add_i32 s5, s40, 4
	s_cmp_ge_u32 s5, s35
	s_cselect_b64 s[30:31], -1, 0
	s_and_b64 vcc, exec, s[30:31]
	s_cbranch_vccnz .LBB0_589
	s_add_i32 s5, s68, s76
	s_mov_b32 s8, m0
	s_mov_b32 m0, s5
	s_nop 0
	global_load_lds_dwordx4 v[194:195], off
	s_mov_b32 m0, s8
